# write-through (sc0 sc1) epilogue stores in F2 and M8 GEMMs: less dirty L2 to flush at the grid barrier; F3 rowpass loads de-serialised
# speedup vs baseline: 1.0041x; 1.0041x over previous
; __device__ __forceinline__ unsigned cvt_pk_bf16(float lo, float hi) { f32x2c v = {lo, hi}; bf16x2c b = __builtin_convertvector(v, bf16x2c); return __builtin_bit_cast(unsigned, b); }
;     __device__ __forceinline__ void operator()(const f32x4 (&acc)[2][2][4][2], const Unit& u, int wr, int wc, int fr, int fq) const {
;         const int row0 = u.pm * BM + wr * 64 + fr, col0 = u.pn * BM + wc * 32 + 8 * fq;
; #pragma unroll
;         for (int ai = 0; ai < 2; ++ai)
; #pragma unroll
;             for (int m = 0; m < 4; ++m) { bf16_t* rowp = O + (size_t)(row0 + ai * HALF + m * 16) * ldc + col0;
; #pragma unroll
;                 for (int bj = 0; bj < 2; ++bj) { const f32x4 v0 = acc[ai][bj][m][0], v1 = acc[ai][bj][m][1];
;                     u32x4 w; w.x = cvt_pk_bf16(v0[0], v0[1]); w.y = cvt_pk_bf16(v0[2], v0[3]); w.z = cvt_pk_bf16(v1[0], v1[1]); w.w = cvt_pk_bf16(v1[2], v1[3]);
;                     *(u32x4*)(rowp + bj * HALF) = w; } }
;     }
.LBB0_697:
	v_lshl_add_u32 v146, s59, 8, v142
	v_lshl_or_b32 v148, s61, 8, v144
	v_ashrrev_i32_e32 v147, 31, v146
	v_ashrrev_i32_e32 v149, 31, v148
	v_lshlrev_b64 v[150:151], 12, v[146:147]
	v_lshl_add_u64 v[150:151], s[28:29], 0, v[150:151]
	v_lshlrev_b64 v[148:149], 1, v[148:149]
	v_lshl_add_u64 v[150:151], v[150:151], 0, v[148:149]
	s_mov_b64 s[42:43], 0x80000
	v_cvt_pk_bf16_f32 v72, v72, v73
	v_cvt_pk_bf16_f32 v73, v74, v75
	v_cvt_pk_bf16_f32 v74, v68, v69
	v_lshl_add_u64 v[68:69], v[150:151], 0, s[42:43]
	s_mov_b32 s42, 0x80000
	v_cvt_pk_bf16_f32 v64, v64, v65
	v_cvt_pk_bf16_f32 v65, v66, v67
	v_cvt_pk_bf16_f32 v66, v60, v61
	v_add_co_u32_e32 v60, vcc, s42, v150
	v_cvt_pk_bf16_f32 v48, v48, v49
	v_cvt_pk_bf16_f32 v49, v50, v51
	v_cvt_pk_bf16_f32 v50, v44, v45
	v_cvt_pk_bf16_f32 v51, v46, v47
	s_mov_b64 s[42:43], 0x90000
	v_addc_co_u32_e32 v61, vcc, 0, v151, vcc
	global_store_dwordx4 v[68:69], v[48:51], off offset:256 sc0 sc1
	v_cvt_pk_bf16_f32 v112, v112, v113
	v_cvt_pk_bf16_f32 v113, v114, v115
	v_lshl_add_u64 v[48:49], v[150:151], 0, s[42:43]
	s_mov_b32 s42, 0x90000
	v_cvt_pk_bf16_f32 v114, v108, v109
	v_or_b32_e32 v108, 16, v146
	v_add_co_u32_e32 v50, vcc, s42, v150
	v_cvt_pk_bf16_f32 v30, v30, v31
	v_cvt_pk_bf16_f32 v31, v32, v33
	v_cvt_pk_bf16_f32 v32, v26, v27
	v_cvt_pk_bf16_f32 v33, v28, v29
	s_mov_b64 s[42:43], 0xa0000
	v_ashrrev_i32_e32 v109, 31, v108
	v_cvt_pk_bf16_f32 v96, v96, v97
	v_cvt_pk_bf16_f32 v97, v98, v99
	v_cvt_pk_bf16_f32 v98, v92, v93
	v_or_b32_e32 v92, 32, v146
	v_addc_co_u32_e32 v51, vcc, 0, v151, vcc
	global_store_dwordx4 v[48:49], v[30:33], off offset:256 sc0 sc1
	v_lshlrev_b64 v[108:109], 12, v[108:109]
	v_ashrrev_i32_e32 v93, 31, v92
	v_lshl_add_u64 v[30:31], v[150:151], 0, s[42:43]
	s_mov_b32 s42, 0xa0000
	v_cvt_pk_bf16_f32 v80, v80, v81
	v_cvt_pk_bf16_f32 v81, v82, v83
	v_cvt_pk_bf16_f32 v82, v76, v77
	v_or_b32_e32 v76, 48, v146
	v_add_co_u32_e32 v32, vcc, s42, v150
	v_cvt_pk_bf16_f32 v14, v14, v15
	v_cvt_pk_bf16_f32 v15, v16, v17
	v_cvt_pk_bf16_f32 v16, v10, v11
	v_cvt_pk_bf16_f32 v17, v12, v13
	s_mov_b64 s[42:43], 0xb0000
	v_cvt_pk_bf16_f32 v115, v110, v111
	v_lshl_add_u64 v[108:109], s[28:29], 0, v[108:109]
	v_lshlrev_b64 v[92:93], 12, v[92:93]
	v_ashrrev_i32_e32 v77, 31, v76
	v_addc_co_u32_e32 v33, vcc, 0, v151, vcc
	global_store_dwordx4 v[30:31], v[14:17], off offset:256 sc0 sc1
	global_store_dwordx4 v[150:151], v[112:115], off offset:256 sc0 sc1
	v_cvt_pk_bf16_f32 v99, v94, v95
	v_lshl_add_u64 v[14:15], v[150:151], 0, s[42:43]
	s_mov_b32 s42, 0xb0000
	v_lshl_add_u64 v[112:113], v[108:109], 0, v[148:149]
	v_lshl_add_u64 v[92:93], s[28:29], 0, v[92:93]
	v_lshlrev_b64 v[76:77], 12, v[76:77]
	v_add_co_u32_e32 v16, vcc, s42, v150
	global_store_dwordx4 v[112:113], v[96:99], off offset:256 sc0 sc1
	v_cvt_pk_bf16_f32 v83, v78, v79
	v_lshl_add_u64 v[76:77], s[28:29], 0, v[76:77]
	v_lshl_add_u64 v[96:97], v[92:93], 0, v[148:149]
	v_addc_co_u32_e32 v17, vcc, 0, v151, vcc
	v_cvt_pk_bf16_f32 v128, v128, v129
	v_cvt_pk_bf16_f32 v129, v130, v131
	v_cvt_pk_bf16_f32 v130, v124, v125
	v_cvt_pk_bf16_f32 v131, v126, v127
	v_cvt_pk_bf16_f32 v108, v120, v121
	v_cvt_pk_bf16_f32 v109, v122, v123
	v_cvt_pk_bf16_f32 v110, v116, v117
	v_cvt_pk_bf16_f32 v111, v118, v119
	v_cvt_pk_bf16_f32 v92, v104, v105
	v_cvt_pk_bf16_f32 v93, v106, v107
	v_cvt_pk_bf16_f32 v94, v100, v101
	v_cvt_pk_bf16_f32 v95, v102, v103
	global_store_dwordx4 v[96:97], v[80:83], off offset:256 sc0 sc1
	v_cvt_pk_bf16_f32 v78, v84, v85
	v_cvt_pk_bf16_f32 v79, v86, v87
	v_lshl_add_u64 v[80:81], v[76:77], 0, v[148:149]
	v_cvt_pk_bf16_f32 v76, v88, v89
	v_cvt_pk_bf16_f32 v77, v90, v91
	v_cvt_pk_bf16_f32 v75, v70, v71
	v_cvt_pk_bf16_f32 v67, v62, v63
	v_cvt_pk_bf16_f32 v44, v56, v57
	v_cvt_pk_bf16_f32 v45, v58, v59
	v_cvt_pk_bf16_f32 v46, v52, v53
	v_cvt_pk_bf16_f32 v47, v54, v55
	v_cvt_pk_bf16_f32 v26, v40, v41
	v_cvt_pk_bf16_f32 v27, v42, v43
	v_cvt_pk_bf16_f32 v28, v36, v37
	v_cvt_pk_bf16_f32 v29, v38, v39
	v_cvt_pk_bf16_f32 v10, v22, v23
	v_cvt_pk_bf16_f32 v11, v24, v25
	v_cvt_pk_bf16_f32 v12, v18, v19
	v_cvt_pk_bf16_f32 v13, v20, v21
	v_cvt_pk_bf16_f32 v6, v6, v7
	v_cvt_pk_bf16_f32 v7, v8, v9
	v_cvt_pk_bf16_f32 v8, v2, v3
	v_cvt_pk_bf16_f32 v9, v4, v5
	s_and_b64 vcc, exec, s[38:39]
	s_mov_b64 s[38:39], -1
	global_store_dwordx4 v[150:151], v[128:131], off sc0 sc1
	global_store_dwordx4 v[112:113], v[108:111], off sc0 sc1
	global_store_dwordx4 v[96:97], v[92:95], off sc0 sc1
	global_store_dwordx4 v[80:81], v[76:79], off sc0 sc1
	global_store_dwordx4 v[80:81], v[72:75], off offset:256 sc0 sc1
	global_store_dwordx4 v[60:61], v[64:67], off sc0 sc1
	global_store_dwordx4 v[50:51], v[44:47], off sc0 sc1
	global_store_dwordx4 v[32:33], v[26:29], off sc0 sc1
	global_store_dwordx4 v[16:17], v[10:13], off sc0 sc1
	global_store_dwordx4 v[14:15], v[6:9], off offset:256 sc0 sc1
	s_cbranch_vccnz .LBB0_682
	s_andn2_b64 vcc, exec, s[26:27]
	s_cbranch_vccnz .LBB0_681
	s_barrier
	s_branch .LBB0_681

; __device__ __forceinline__ unsigned cvt_pk_bf16(float lo, float hi) { f32x2c v = {lo, hi}; bf16x2c b = __builtin_convertvector(v, bf16x2c); return __builtin_bit_cast(unsigned, b); }
;     __device__ __forceinline__ void operator()(const f32x4 (&acc)[2][2][4][2], const Unit& u, int wr, int wc, int fr, int fq) const {
;         const int row0 = u.pm * BM + wr * 64 + fr, col0 = u.pn * BM + wc * 32 + 8 * fq;
; #pragma unroll
;         for (int ai = 0; ai < 2; ++ai)
; #pragma unroll
;             for (int m = 0; m < 4; ++m) { bf16_t* rowp = O + (size_t)(row0 + ai * HALF + m * 16) * ldc + col0;
; #pragma unroll
;                 for (int bj = 0; bj < 2; ++bj) { const f32x4 v0 = acc[ai][bj][m][0] * sc, v1 = acc[ai][bj][m][1] * sc;
;                     u32x4 w; w.x = cvt_pk_bf16(v0[0], v0[1]); w.y = cvt_pk_bf16(v0[2], v0[3]); w.z = cvt_pk_bf16(v1[0], v1[1]); w.w = cvt_pk_bf16(v1[2], v1[3]);
;                     *(u32x4*)(rowp + bj * HALF) = w; } }
;     }
.LBB0_729:
	v_lshl_add_u32 v8, s55, 8, v208
	v_lshl_or_b32 v2, s56, 8, v210
	v_ashrrev_i32_e32 v9, 31, v8
	v_ashrrev_i32_e32 v3, 31, v2
	v_lshlrev_b64 v[4:5], 12, v[8:9]
	v_lshl_add_u64 v[4:5], s[18:19], 0, v[4:5]
	v_lshlrev_b64 v[10:11], 1, v[2:3]
	v_mov_b32_e32 v193, v192
	v_lshl_add_u64 v[2:3], v[4:5], 0, v[10:11]
	v_pk_mul_f32 v[6:7], v[192:193], v[162:163]
	v_pk_mul_f32 v[4:5], v[194:195], v[160:161]
	v_pk_mul_f32 v[12:13], v[192:193], v[158:159]
	v_pk_mul_f32 v[14:15], v[194:195], v[156:157]
	v_cvt_pk_bf16_f32 v4, v4, v5
	v_cvt_pk_bf16_f32 v5, v6, v7
	v_cvt_pk_bf16_f32 v6, v14, v15
	v_cvt_pk_bf16_f32 v7, v12, v13
	s_nop 15
	s_nop 15
	global_store_dwordx4 v[2:3], v[4:7], off sc0 sc1
	v_pk_mul_f32 v[12:13], v[192:193], v[142:143]
	v_pk_mul_f32 v[14:15], v[194:195], v[140:141]
	v_pk_mul_f32 v[6:7], v[192:193], v[150:151]
	v_pk_mul_f32 v[4:5], v[194:195], v[148:149]
	v_pk_mul_f32 v[16:17], v[194:195], v[144:145]
	v_cvt_pk_bf16_f32 v4, v4, v5
	v_cvt_pk_bf16_f32 v5, v6, v7
	v_cvt_pk_bf16_f32 v6, v14, v15
	v_cvt_pk_bf16_f32 v7, v12, v13
	global_store_dwordx4 v[2:3], v[4:7], off offset:256 sc0 sc1
	v_pk_mul_f32 v[14:15], v[192:193], v[146:147]
	s_mov_b64 s[40:41], 0x80000
	v_or_b32_e32 v4, 16, v8
	v_ashrrev_i32_e32 v5, 31, v4
	v_lshlrev_b64 v[4:5], 12, v[4:5]
	v_lshl_add_u64 v[4:5], s[18:19], 0, v[4:5]
	v_lshl_add_u64 v[12:13], v[4:5], 0, v[10:11]
	v_pk_mul_f32 v[6:7], v[192:193], v[154:155]
	v_pk_mul_f32 v[4:5], v[194:195], v[152:153]
	s_nop 0
	v_cvt_pk_bf16_f32 v4, v4, v5
	v_cvt_pk_bf16_f32 v5, v6, v7
	v_cvt_pk_bf16_f32 v6, v16, v17
	v_cvt_pk_bf16_f32 v7, v14, v15
	global_store_dwordx4 v[12:13], v[4:7], off sc0 sc1
	v_pk_mul_f32 v[14:15], v[192:193], v[126:127]
	v_pk_mul_f32 v[16:17], v[194:195], v[124:125]
	v_pk_mul_f32 v[6:7], v[192:193], v[134:135]
	v_pk_mul_f32 v[4:5], v[194:195], v[132:133]
	s_nop 0
	v_cvt_pk_bf16_f32 v4, v4, v5
	v_cvt_pk_bf16_f32 v5, v6, v7
	v_cvt_pk_bf16_f32 v6, v16, v17
	v_cvt_pk_bf16_f32 v7, v14, v15
	global_store_dwordx4 v[12:13], v[4:7], off offset:256 sc0 sc1
	v_pk_mul_f32 v[14:15], v[192:193], v[130:131]
	v_pk_mul_f32 v[16:17], v[194:195], v[128:129]
	v_or_b32_e32 v4, 32, v8
	v_ashrrev_i32_e32 v5, 31, v4
	v_lshlrev_b64 v[4:5], 12, v[4:5]
	v_lshl_add_u64 v[4:5], s[18:19], 0, v[4:5]
	v_lshl_add_u64 v[12:13], v[4:5], 0, v[10:11]
	v_pk_mul_f32 v[6:7], v[192:193], v[138:139]
	v_pk_mul_f32 v[4:5], v[194:195], v[136:137]
	s_nop 0
	v_cvt_pk_bf16_f32 v4, v4, v5
	v_cvt_pk_bf16_f32 v5, v6, v7
	v_cvt_pk_bf16_f32 v6, v16, v17
	v_cvt_pk_bf16_f32 v7, v14, v15
	global_store_dwordx4 v[12:13], v[4:7], off sc0 sc1
	v_pk_mul_f32 v[14:15], v[192:193], v[110:111]
	v_pk_mul_f32 v[16:17], v[194:195], v[108:109]
	v_pk_mul_f32 v[6:7], v[192:193], v[118:119]
	v_pk_mul_f32 v[4:5], v[194:195], v[116:117]
	s_nop 0
	v_cvt_pk_bf16_f32 v4, v4, v5
	v_cvt_pk_bf16_f32 v5, v6, v7
	v_cvt_pk_bf16_f32 v6, v16, v17
	v_cvt_pk_bf16_f32 v7, v14, v15
	global_store_dwordx4 v[12:13], v[4:7], off offset:256 sc0 sc1
	v_pk_mul_f32 v[12:13], v[194:195], v[112:113]
	s_nop 0
	v_or_b32_e32 v4, 48, v8
	v_ashrrev_i32_e32 v5, 31, v4
	v_lshlrev_b64 v[4:5], 12, v[4:5]
	v_lshl_add_u64 v[4:5], s[18:19], 0, v[4:5]
	v_lshl_add_u64 v[8:9], v[4:5], 0, v[10:11]
	v_pk_mul_f32 v[6:7], v[192:193], v[122:123]
	v_pk_mul_f32 v[4:5], v[194:195], v[120:121]
	v_pk_mul_f32 v[10:11], v[192:193], v[114:115]
	v_cvt_pk_bf16_f32 v4, v4, v5
	v_cvt_pk_bf16_f32 v5, v6, v7
	v_cvt_pk_bf16_f32 v6, v12, v13
	v_cvt_pk_bf16_f32 v7, v10, v11
	global_store_dwordx4 v[8:9], v[4:7], off sc0 sc1
	v_pk_mul_f32 v[10:11], v[192:193], v[102:103]
	v_pk_mul_f32 v[12:13], v[194:195], v[100:101]
	v_pk_mul_f32 v[6:7], v[192:193], v[106:107]
	v_pk_mul_f32 v[4:5], v[194:195], v[104:105]
	s_nop 0
	v_cvt_pk_bf16_f32 v4, v4, v5
	v_cvt_pk_bf16_f32 v5, v6, v7
	v_cvt_pk_bf16_f32 v6, v12, v13
; __device__ __forceinline__ unsigned cvt_pk_bf16(float lo, float hi) { f32x2c v = {lo, hi}; bf16x2c b = __builtin_convertvector(v, bf16x2c); return __builtin_bit_cast(unsigned, b); }
;     __device__ __forceinline__ void operator()(const f32x4 (&acc)[2][2][4][2], const Unit& u, int wr, int wc, int fr, int fq) const {
;         const int row0 = u.pm * BM + wr * 64 + fr, col0 = u.pn * BM + wc * 32 + 8 * fq;
; #pragma unroll
;         for (int ai = 0; ai < 2; ++ai)
; #pragma unroll
;             for (int m = 0; m < 4; ++m) { bf16_t* rowp = O + (size_t)(row0 + ai * HALF + m * 16) * ldc + col0;
; #pragma unroll
;                 for (int bj = 0; bj < 2; ++bj) { const f32x4 v0 = acc[ai][bj][m][0] * sc, v1 = acc[ai][bj][m][1] * sc;
;                     u32x4 w; w.x = cvt_pk_bf16(v0[0], v0[1]); w.y = cvt_pk_bf16(v0[2], v0[3]); w.z = cvt_pk_bf16(v1[0], v1[1]); w.w = cvt_pk_bf16(v1[2], v1[3]);
;                     *(u32x4*)(rowp + bj * HALF) = w; } }
;     }
	v_cvt_pk_bf16_f32 v7, v10, v11
	global_store_dwordx4 v[8:9], v[4:7], off offset:256 sc0 sc1
	v_lshl_add_u64 v[8:9], v[2:3], 0, s[40:41]
	v_pk_mul_f32 v[10:11], v[192:193], v[94:95]
	v_pk_mul_f32 v[6:7], v[192:193], v[98:99]
	v_pk_mul_f32 v[4:5], v[194:195], v[96:97]
	s_mov_b32 s40, 0x80000
	v_pk_mul_f32 v[12:13], v[194:195], v[92:93]
	v_cvt_pk_bf16_f32 v4, v4, v5
	v_cvt_pk_bf16_f32 v5, v6, v7
	v_cvt_pk_bf16_f32 v7, v10, v11
	v_add_co_u32_e32 v10, vcc, s40, v2
	v_cvt_pk_bf16_f32 v6, v12, v13
	s_nop 0
	v_addc_co_u32_e32 v11, vcc, 0, v3, vcc
	global_store_dwordx4 v[10:11], v[4:7], off sc0 sc1
	v_pk_mul_f32 v[10:11], v[192:193], v[78:79]
	v_pk_mul_f32 v[12:13], v[194:195], v[76:77]
	v_pk_mul_f32 v[6:7], v[192:193], v[86:87]
	v_pk_mul_f32 v[4:5], v[194:195], v[84:85]
	s_mov_b64 s[40:41], 0x90000
	v_cvt_pk_bf16_f32 v4, v4, v5
	v_cvt_pk_bf16_f32 v5, v6, v7
	v_cvt_pk_bf16_f32 v6, v12, v13
	v_cvt_pk_bf16_f32 v7, v10, v11
	global_store_dwordx4 v[8:9], v[4:7], off offset:256 sc0 sc1
	v_lshl_add_u64 v[8:9], v[2:3], 0, s[40:41]
	v_pk_mul_f32 v[10:11], v[192:193], v[82:83]
	v_pk_mul_f32 v[6:7], v[192:193], v[90:91]
	v_pk_mul_f32 v[4:5], v[194:195], v[88:89]
	s_mov_b32 s40, 0x90000
	v_pk_mul_f32 v[12:13], v[194:195], v[80:81]
	v_cvt_pk_bf16_f32 v4, v4, v5
	v_cvt_pk_bf16_f32 v5, v6, v7
	v_cvt_pk_bf16_f32 v7, v10, v11
	v_add_co_u32_e32 v10, vcc, s40, v2
	v_cvt_pk_bf16_f32 v6, v12, v13
	s_nop 0
	v_addc_co_u32_e32 v11, vcc, 0, v3, vcc
	global_store_dwordx4 v[10:11], v[4:7], off sc0 sc1
	v_pk_mul_f32 v[10:11], v[192:193], v[62:63]
	v_pk_mul_f32 v[12:13], v[194:195], v[60:61]
	v_pk_mul_f32 v[6:7], v[192:193], v[70:71]
	v_pk_mul_f32 v[4:5], v[194:195], v[68:69]
	s_mov_b64 s[40:41], 0xa0000
	v_cvt_pk_bf16_f32 v4, v4, v5
	v_cvt_pk_bf16_f32 v5, v6, v7
	v_cvt_pk_bf16_f32 v6, v12, v13
	v_cvt_pk_bf16_f32 v7, v10, v11
	global_store_dwordx4 v[8:9], v[4:7], off offset:256 sc0 sc1
	v_lshl_add_u64 v[8:9], v[2:3], 0, s[40:41]
	v_pk_mul_f32 v[10:11], v[192:193], v[66:67]
	v_pk_mul_f32 v[6:7], v[192:193], v[74:75]
	v_pk_mul_f32 v[4:5], v[194:195], v[72:73]
	s_mov_b32 s40, 0xa0000
	v_pk_mul_f32 v[12:13], v[194:195], v[64:65]
	v_cvt_pk_bf16_f32 v4, v4, v5
	v_cvt_pk_bf16_f32 v5, v6, v7
	v_cvt_pk_bf16_f32 v7, v10, v11
	v_add_co_u32_e32 v10, vcc, s40, v2
	v_cvt_pk_bf16_f32 v6, v12, v13
	s_nop 0
	v_addc_co_u32_e32 v11, vcc, 0, v3, vcc
	global_store_dwordx4 v[10:11], v[4:7], off sc0 sc1
	v_pk_mul_f32 v[10:11], v[192:193], v[46:47]
	v_pk_mul_f32 v[12:13], v[194:195], v[44:45]
	v_pk_mul_f32 v[6:7], v[192:193], v[54:55]
	v_pk_mul_f32 v[4:5], v[194:195], v[52:53]
	s_mov_b64 s[40:41], 0xb0000
	v_cvt_pk_bf16_f32 v4, v4, v5
	v_cvt_pk_bf16_f32 v5, v6, v7
	v_cvt_pk_bf16_f32 v6, v12, v13
	v_cvt_pk_bf16_f32 v7, v10, v11
	global_store_dwordx4 v[8:9], v[4:7], off offset:256 sc0 sc1
	v_lshl_add_u64 v[8:9], v[2:3], 0, s[40:41]
	s_mov_b32 s40, 0xb0000
	v_pk_mul_f32 v[6:7], v[192:193], v[58:59]
	v_pk_mul_f32 v[4:5], v[194:195], v[56:57]
	v_pk_mul_f32 v[10:11], v[192:193], v[50:51]
	v_pk_mul_f32 v[12:13], v[194:195], v[48:49]
	v_add_co_u32_e32 v2, vcc, s40, v2
	v_cvt_pk_bf16_f32 v4, v4, v5
	v_cvt_pk_bf16_f32 v5, v6, v7
	v_cvt_pk_bf16_f32 v6, v12, v13
	v_cvt_pk_bf16_f32 v7, v10, v11
	v_addc_co_u32_e32 v3, vcc, 0, v3, vcc
	global_store_dwordx4 v[2:3], v[4:7], off sc0 sc1
	v_pk_mul_f32 v[2:3], v[194:195], v[40:41]
	v_pk_mul_f32 v[10:11], v[194:195], v[36:37]
	v_pk_mul_f32 v[4:5], v[192:193], v[42:43]
	v_pk_mul_f32 v[6:7], v[192:193], v[38:39]
	v_cvt_pk_bf16_f32 v2, v2, v3
	v_cvt_pk_bf16_f32 v3, v4, v5
	v_cvt_pk_bf16_f32 v4, v10, v11
	v_cvt_pk_bf16_f32 v5, v6, v7
	s_and_b64 vcc, exec, s[38:39]
	s_mov_b64 s[38:39], -1
	global_store_dwordx4 v[8:9], v[2:5], off offset:256 sc0 sc1
	s_cbranch_vccnz .LBB0_714
	s_andn2_b64 vcc, exec, s[26:27]
	s_cbranch_vccnz .LBB0_713
	s_barrier
	s_branch .LBB0_713

; #define GAS __attribute__((address_space(1)))
; __device__ __forceinline__ void rowpass(const Frame& F, const float* xin32, const unsigned short* xih, const unsigned char* xil, const bf16* Y, float* xo32, unsigned short* xoh, unsigned char* xol, ...
;     ...
;         else { const GAS v4u* h0 = (const GAS v4u*)(xih + (size_t)m * D) + ln; const GAS v4u* h1 = (const GAS v4u*)(xih + (size_t)m1 * D) + ln;
;             const GAS v2u* l0 = (const GAS v2u*)(xil + (size_t)m * D) + ln; const GAS v2u* l1 = (const GAS v2u*)(xil + (size_t)m1 * D) + ln;
;             v4u a0[4], a1[4]; v2u b0[4], b1[4];
; #pragma unroll
;             for (int j = 0; j < 4; ++j) { a0[j] = __builtin_nontemporal_load(h0 + 64 * j); a1[j] = __builtin_nontemporal_load(h1 + 64 * j); b0[j] = __builtin_nontemporal_load(l0 + 64 * j); b1[j] = __builtin_nontemporal_load(l1 + 64 * j); }
; #pragma unroll
;             for (int j = 0; j < 4; ++j) { x0[2 * j] = x_unpack4(a0[j].x, a0[j].y, b0[j].x); x0[2 * j + 1] = x_unpack4(a0[j].z, a0[j].w, b0[j].y); x1[2 * j] = x_unpack4(a1[j].x, a1[j].y, b1[j].x); x1[2 * j + 1] = x_unpack4(a1[j].z, a1[j].w, b1[j].y); } }
;         if (Y) {
;             const GAS v4u* yr0 = (const GAS v4u*)(Y + (size_t)m * D) + ln; const GAS v4u* yr1 = (const GAS v4u*)(Y + (size_t)m1 * D) + ln;
;             v4u y0[4], y1[4]; float s0 = 0.f, s1 = 0.f;
; #pragma unroll
;             for (int j = 0; j < 4; ++j) { y0[j] = __builtin_nontemporal_load(yr0 + 64 * j); y1[j] = __builtin_nontemporal_load(yr1 + 64 * j); }
.LBB0_809:
	s_lshl_b64 s[82:83], s[40:41], 11
	s_mov_b32 s6, 0x52c00000
	v_add_co_u32_e32 v76, vcc, s6, v160
	v_lshl_add_u64 v[78:79], s[82:83], 1, v[148:149]
	s_nop 0
	v_addc_co_u32_e32 v77, vcc, 0, v161, vcc
	global_load_dwordx4 v[242:245], v[76:77], off nt
	global_load_dwordx4 v[246:249], v[78:79], off nt
	global_load_dwordx4 v[250:253], v[76:77], off offset:1024 nt
	global_load_dwordx4 v[96:99], v[78:79], off offset:1024 nt
	global_load_dwordx4 v[196:199], v[76:77], off offset:2048 nt
	global_load_dwordx4 v[206:209], v[78:79], off offset:2048 nt
	global_load_dwordx4 v[216:219], v[76:77], off offset:3072 nt
	global_load_dwordx4 v[238:241], v[78:79], off offset:3072 nt
	v_add_co_u32_e32 v50, vcc, 0x3ac00000, v160
	s_lshl_b64 s[12:13], s[40:41], 12
	s_nop 0
	v_addc_co_u32_e32 v51, vcc, 0, v161, vcc
	v_lshl_add_u64 v[40:41], v[144:145], 0, s[12:13]
	global_load_dwordx4 v[36:39], v[50:51], off nt
	global_load_dwordx4 v[44:47], v[40:41], off nt
	v_lshl_add_u64 v[42:43], s[18:19], 0, v[158:159]
	v_add_co_u32_e32 v42, vcc, 0x3ec00000, v42
	s_nop 0
	v_addc_co_u32_e32 v43, vcc, 0, v43, vcc
	v_lshl_add_u64 v[48:49], v[146:147], 0, s[82:83]
	global_load_dwordx2 v[52:53], v[42:43], off nt
	global_load_dwordx2 v[58:59], v[48:49], off nt
	global_load_dwordx4 v[60:63], v[50:51], off offset:1024 nt
	global_load_dwordx4 v[64:67], v[40:41], off offset:1024 nt
	global_load_dwordx2 v[94:95], v[42:43], off offset:512 nt
	global_load_dwordx2 v[92:93], v[48:49], off offset:512 nt
	global_load_dwordx4 v[72:75], v[50:51], off offset:2048 nt
	global_load_dwordx4 v[68:71], v[40:41], off offset:2048 nt
	global_load_dwordx2 v[90:91], v[42:43], off offset:1024 nt
	global_load_dwordx2 v[88:89], v[48:49], off offset:1024 nt
	global_load_dwordx4 v[80:83], v[50:51], off offset:3072 nt
	global_load_dwordx4 v[76:79], v[40:41], off offset:3072 nt
	global_load_dwordx2 v[86:87], v[42:43], off offset:1536 nt
	global_load_dwordx2 v[84:85], v[48:49], off offset:1536 nt
	s_waitcnt vmcnt(13)
	v_lshlrev_b32_e32 v40, 8, v52
	v_lshrrev_b32_e32 v48, 16, v53
	v_perm_b32 v40, v36, v40, s88
	v_perm_b32 v41, v36, v52, s89
	v_lshrrev_b32_e32 v36, 8, v52
	v_perm_b32 v42, v37, v36, s88
	v_lshrrev_b32_e32 v36, 16, v52
	v_perm_b32 v43, v37, v36, s89
	v_lshlrev_b32_e32 v36, 8, v53
	v_perm_b32 v36, v38, v36, s88
	v_perm_b32 v37, v38, v53, s89
	v_lshrrev_b32_e32 v38, 8, v53
	v_perm_b32 v38, v39, v38, s88
	v_perm_b32 v39, v39, v48, s89
	s_waitcnt vmcnt(12)
	v_lshlrev_b32_e32 v48, 8, v58
	v_perm_b32 v52, v44, v48, s88
	v_perm_b32 v53, v44, v58, s89
	v_lshrrev_b32_e32 v44, 8, v58
	v_perm_b32 v54, v45, v44, s88
	v_lshrrev_b32_e32 v44, 16, v58
	v_perm_b32 v55, v45, v44, s89
	v_lshlrev_b32_e32 v44, 8, v59
	v_perm_b32 v56, v46, v44, s88
	v_lshrrev_b32_e32 v44, 8, v59
	v_perm_b32 v58, v47, v44, s88
	v_lshrrev_b32_e32 v44, 16, v59
	v_perm_b32 v57, v46, v59, s89
	v_perm_b32 v59, v47, v44, s89
	s_waitcnt vmcnt(9)
	v_lshlrev_b32_e32 v44, 8, v94
	v_perm_b32 v48, v60, v44, s88
	v_lshrrev_b32_e32 v44, 8, v94
	v_perm_b32 v50, v61, v44, s88
	v_lshrrev_b32_e32 v44, 16, v94
	v_perm_b32 v49, v60, v94, s89
	v_perm_b32 v51, v61, v44, s89
	v_lshlrev_b32_e32 v44, 8, v95
	v_lshrrev_b32_e32 v46, 8, v95
	v_lshrrev_b32_e32 v47, 16, v95
	s_waitcnt vmcnt(8)
	v_lshlrev_b32_e32 v60, 8, v92
	v_perm_b32 v44, v62, v44, s88
	v_perm_b32 v45, v62, v95, s89
	v_perm_b32 v46, v63, v46, s88
	v_perm_b32 v47, v63, v47, s89
	v_perm_b32 v60, v64, v60, s88
	v_perm_b32 v61, v64, v92, s89
	v_lshrrev_b32_e32 v62, 8, v92
	v_lshrrev_b32_e32 v63, 16, v92
	v_lshlrev_b32_e32 v64, 8, v93
	v_perm_b32 v62, v65, v62, s88
	v_perm_b32 v63, v65, v63, s89
	v_perm_b32 v64, v66, v64, s88
	v_perm_b32 v65, v66, v93, s89
	v_lshrrev_b32_e32 v66, 8, v93
	v_lshrrev_b32_e32 v92, 16, v93
	v_perm_b32 v66, v67, v66, s88
	v_perm_b32 v67, v67, v92, s89
	s_waitcnt vmcnt(5)
	v_lshlrev_b32_e32 v92, 8, v90
	v_perm_b32 v104, v72, v92, s88
	v_perm_b32 v105, v72, v90, s89
	v_lshrrev_b32_e32 v72, 8, v90
	v_perm_b32 v106, v73, v72, s88
	v_lshrrev_b32_e32 v72, 16, v90
	v_perm_b32 v107, v73, v72, s89
	v_lshlrev_b32_e32 v72, 8, v91
	v_perm_b32 v100, v74, v72, s88
	v_lshrrev_b32_e32 v72, 8, v91
	v_perm_b32 v102, v75, v72, s88
	v_lshrrev_b32_e32 v72, 16, v91
	v_perm_b32 v103, v75, v72, s89
	s_waitcnt vmcnt(4)
	v_lshlrev_b32_e32 v72, 8, v88
	v_perm_b32 v120, v68, v72, s88
	v_perm_b32 v121, v68, v88, s89
	v_lshrrev_b32_e32 v68, 8, v88
	v_perm_b32 v122, v69, v68, s88
	v_lshrrev_b32_e32 v68, 16, v88
	v_perm_b32 v123, v69, v68, s89
	v_lshlrev_b32_e32 v68, 8, v89
	v_perm_b32 v124, v70, v68, s88
	v_lshrrev_b32_e32 v68, 8, v89
	v_perm_b32 v126, v71, v68, s88
	v_lshrrev_b32_e32 v68, 16, v89
	v_perm_b32 v127, v71, v68, s89
	s_waitcnt vmcnt(1)
	v_lshlrev_b32_e32 v68, 8, v86
	v_perm_b32 v112, v80, v68, s88
	v_lshrrev_b32_e32 v68, 8, v86
	v_perm_b32 v114, v81, v68, s88
	v_lshrrev_b32_e32 v68, 16, v86
	v_perm_b32 v115, v81, v68, s89
	v_lshlrev_b32_e32 v68, 8, v87
	v_perm_b32 v108, v82, v68, s88
	v_lshrrev_b32_e32 v68, 8, v87
	v_perm_b32 v110, v83, v68, s88
	v_lshrrev_b32_e32 v68, 16, v87
	v_perm_b32 v111, v83, v68, s89
	s_waitcnt vmcnt(0)
	v_lshlrev_b32_e32 v68, 8, v84
	v_perm_b32 v128, v76, v68, s88
	v_lshrrev_b32_e32 v68, 8, v84
	v_perm_b32 v130, v77, v68, s88
	v_lshrrev_b32_e32 v68, 16, v84
	v_perm_b32 v131, v77, v68, s89
	v_lshlrev_b32_e32 v68, 8, v85
	v_perm_b32 v116, v78, v68, s88
	v_lshrrev_b32_e32 v68, 8, v85
	v_perm_b32 v118, v79, v68, s88
	v_lshrrev_b32_e32 v68, 16, v85
	v_perm_b32 v101, v74, v91, s89
	v_perm_b32 v125, v70, v89, s89
	v_perm_b32 v113, v80, v86, s89
	v_perm_b32 v109, v82, v87, s89
	v_perm_b32 v129, v76, v84, s89
	v_perm_b32 v117, v78, v85, s89
	v_perm_b32 v119, v79, v68, s89
	s_branch .Lrp3_ydone
; #define GAS __attribute__((address_space(1)))
; __device__ __forceinline__ f32x4 bf4(const unsigned a, const unsigned b) { return (f32x4){blo(a), bhi(a), blo(b), bhi(b)}; }
; __device__ __forceinline__ void rowpass(const Frame& F, const float* xin32, const unsigned short* xih, const unsigned char* xil, const bf16* Y, float* xo32, unsigned short* xoh, unsigned char* xol, ...
;     ...
;         if (Y) {
;             const GAS v4u* yr0 = (const GAS v4u*)(Y + (size_t)m * D) + ln; const GAS v4u* yr1 = (const GAS v4u*)(Y + (size_t)m1 * D) + ln;
;             v4u y0[4], y1[4]; float s0 = 0.f, s1 = 0.f;
; #pragma unroll
;             for (int j = 0; j < 4; ++j) { y0[j] = __builtin_nontemporal_load(yr0 + 64 * j); y1[j] = __builtin_nontemporal_load(yr1 + 64 * j); }
; #pragma unroll
;             for (int j = 0; j < 4; ++j) { const f32x4 a = bf4(y0[j].x, y0[j].y), b = bf4(y0[j].z, y0[j].w), c = bf4(y1[j].x, y1[j].y), d = bf4(y1[j].z, y1[j].w);
;                 s0 += ((a.x * a.x + a.y * a.y) + (a.z * a.z + a.w * a.w)) + ((b.x * b.x + b.y * b.y) + (b.z * b.z + b.w * b.w));
;                 s1 += ((c.x * c.x + c.y * c.y) + (c.z * c.z + c.w * c.w)) + ((d.x * d.x + d.y * d.y) + (d.z * d.z + d.w * d.w)); }
; #pragma unroll
;             for (int o = 1; o < 64; o <<= 1) { s0 += __shfl_xor(s0, o); s1 += __shfl_xor(s1, o); }
;             const float r0 = scale * rsqrtf(s0 * (1.f / D) + EPS), r1 = scale * rsqrtf(s1 * (1.f / D) + EPS);
.LBB0_810:
	s_mov_b32 s6, 0x52c00000
	v_add_co_u32_e32 v76, vcc, s6, v160
	v_lshl_add_u64 v[78:79], s[82:83], 1, v[148:149]
	s_nop 0
	v_addc_co_u32_e32 v77, vcc, 0, v161, vcc
	global_load_dwordx4 v[242:245], v[76:77], off nt
	global_load_dwordx4 v[246:249], v[78:79], off nt
	global_load_dwordx4 v[250:253], v[76:77], off offset:1024 nt
	global_load_dwordx4 v[96:99], v[78:79], off offset:1024 nt
	global_load_dwordx4 v[196:199], v[76:77], off offset:2048 nt
	global_load_dwordx4 v[206:209], v[78:79], off offset:2048 nt
	global_load_dwordx4 v[216:219], v[76:77], off offset:3072 nt
	global_load_dwordx4 v[238:241], v[78:79], off offset:3072 nt
.Lrp3_ydone:
	s_mov_b32 s6, 0x3a000000
	s_waitcnt vmcnt(0)
	v_lshlrev_b32_e32 v95, 16, v247
	v_lshlrev_b32_e32 v94, 16, v246
	v_and_b32_e32 v93, 0xffff0000, v247
	v_and_b32_e32 v92, 0xffff0000, v246
	v_lshlrev_b32_e32 v83, 16, v249
	v_and_b32_e32 v85, 0xffff0000, v243
	v_and_b32_e32 v84, 0xffff0000, v242
	v_and_b32_e32 v77, 0xffff0000, v245
	v_and_b32_e32 v76, 0xffff0000, v244
	v_lshlrev_b32_e32 v87, 16, v243
	v_lshlrev_b32_e32 v86, 16, v242
	v_lshlrev_b32_e32 v79, 16, v245
	v_lshlrev_b32_e32 v78, 16, v244
	v_lshlrev_b32_e32 v82, 16, v248
	v_and_b32_e32 v81, 0xffff0000, v249
	v_and_b32_e32 v80, 0xffff0000, v248
	v_lshlrev_b32_e32 v75, 16, v251
	v_lshlrev_b32_e32 v74, 16, v250
	v_and_b32_e32 v73, 0xffff0000, v251
	v_and_b32_e32 v72, 0xffff0000, v250
	v_lshlrev_b32_e32 v71, 16, v253
	v_lshlrev_b32_e32 v70, 16, v252
	v_and_b32_e32 v69, 0xffff0000, v253
	v_and_b32_e32 v68, 0xffff0000, v252
	v_and_b32_e32 v201, 0xffff0000, v97
	v_and_b32_e32 v200, 0xffff0000, v96
	v_pk_mul_f32 v[88:89], v[84:85], v[84:85]
	v_pk_mul_f32 v[90:91], v[76:77], v[76:77]
	v_lshlrev_b32_e32 v205, 16, v97
	v_lshlrev_b32_e32 v204, 16, v96
	v_lshlrev_b32_e32 v214, 16, v216
	v_and_b32_e32 v215, 0xffff0000, v216
	v_pk_mul_f32 v[222:223], v[200:201], v[200:201]
	v_pk_fma_f32 v[88:89], v[86:87], v[86:87], v[88:89]
	v_pk_fma_f32 v[90:91], v[78:79], v[78:79], v[90:91]
	v_lshlrev_b32_e32 v212, 16, v217
	v_and_b32_e32 v213, 0xffff0000, v217
	v_pk_mul_f32 v[216:217], v[72:73], v[72:73]
	v_pk_fma_f32 v[248:249], v[204:205], v[204:205], v[222:223]
	v_lshlrev_b32_e32 v222, 16, v238
	v_and_b32_e32 v223, 0xffff0000, v238
	v_mul_f32_e32 v237, v214, v214
	v_mul_f32_e32 v238, v215, v215
	v_pk_add_f32 v[88:89], v[88:89], v[88:89] op_sel:[0,1] op_sel_hi:[1,0]
	v_pk_add_f32 v[90:91], v[90:91], v[90:91] op_sel:[0,1] op_sel_hi:[1,0]
	v_pk_mul_f32 v[220:221], v[68:69], v[68:69]
	v_pk_fma_f32 v[244:245], v[74:75], v[74:75], v[216:217]
	v_mov_b32_e32 v89, v237
	v_mov_b32_e32 v91, v238
	v_pk_fma_f32 v[246:247], v[70:71], v[70:71], v[220:221]
	v_lshlrev_b32_e32 v220, 16, v239
	v_and_b32_e32 v221, 0xffff0000, v239
	v_mul_f32_e32 v239, v212, v212
	v_pk_add_f32 v[88:89], v[88:89], v[90:91]
	v_pk_add_f32 v[90:91], v[244:245], v[244:245] op_sel:[0,1] op_sel_hi:[1,0]
	v_lshlrev_b32_e32 v190, 16, v196
	v_and_b32_e32 v191, 0xffff0000, v196
	v_lshlrev_b32_e32 v188, 16, v197
	v_and_b32_e32 v189, 0xffff0000, v197
	v_lshlrev_b32_e32 v196, 16, v208
	v_and_b32_e32 v197, 0xffff0000, v208
	v_lshlrev_b32_e32 v202, 16, v209
	v_and_b32_e32 v203, 0xffff0000, v209
	v_lshlrev_b32_e32 v210, 16, v218
	v_and_b32_e32 v211, 0xffff0000, v218
	v_lshlrev_b32_e32 v208, 16, v219
	v_and_b32_e32 v209, 0xffff0000, v219
	v_lshlrev_b32_e32 v218, 16, v240
	v_and_b32_e32 v219, 0xffff0000, v240
	v_mul_f32_e32 v240, v213, v213
	v_mov_b32_e32 v91, v239
	v_pk_add_f32 v[238:239], v[246:247], v[246:247] op_sel:[0,1] op_sel_hi:[1,0]
	v_lshlrev_b32_e32 v216, 16, v241
	v_mov_b32_e32 v239, v240
	v_pk_add_f32 v[90:91], v[90:91], v[238:239]
	v_mul_f32_e32 v238, v189, v189
	v_pk_add_f32 v[88:89], v[88:89], v[90:91]
	v_mul_f32_e32 v90, v191, v191
	v_and_b32_e32 v217, 0xffff0000, v241
	v_mul_f32_e32 v241, v210, v210
	v_mul_f32_e32 v250, v211, v211
	v_pk_fma_f32 v[90:91], v[190:191], v[190:191], v[90:91] op_sel_hi:[1,1,0]
	v_pk_fma_f32 v[238:239], v[188:189], v[188:189], v[238:239] op_sel_hi:[1,1,0]
	v_and_b32_e32 v187, 0xffff0000, v198
	v_and_b32_e32 v163, 0xffff0000, v199
	v_mov_b32_e32 v91, v241
	v_mov_b32_e32 v239, v250
	v_lshlrev_b32_e32 v186, 16, v198
	v_lshlrev_b32_e32 v162, 16, v199
	v_pk_add_f32 v[90:91], v[90:91], v[238:239]
	v_mul_f32_e32 v238, v187, v187
	v_mul_f32_e32 v240, v163, v163
	v_mul_f32_e32 v251, v208, v208
	v_mul_f32_e32 v252, v209, v209
	v_pk_fma_f32 v[238:239], v[186:187], v[186:187], v[238:239] op_sel_hi:[1,1,0]
	v_pk_fma_f32 v[240:241], v[162:163], v[162:163], v[240:241] op_sel_hi:[1,1,0]
	v_mov_b32_e32 v239, v251
	v_mov_b32_e32 v241, v252
	v_lshlrev_b32_e32 v195, 16, v99
	v_lshlrev_b32_e32 v194, 16, v98
	v_and_b32_e32 v193, 0xffff0000, v99
	v_and_b32_e32 v192, 0xffff0000, v98
	v_pk_mul_f32 v[96:97], v[92:93], v[92:93]
	v_pk_mul_f32 v[98:99], v[80:81], v[80:81]
	v_pk_add_f32 v[238:239], v[238:239], v[240:241]
	v_pk_fma_f32 v[96:97], v[94:95], v[94:95], v[96:97]
	v_pk_fma_f32 v[98:99], v[82:83], v[82:83], v[98:99]
	v_pk_add_f32 v[90:91], v[90:91], v[238:239]
	v_pk_mul_f32 v[242:243], v[192:193], v[192:193]
	v_pk_add_f32 v[88:89], v[88:89], v[90:91]
	v_mul_f32_e32 v237, v222, v222
	v_mul_f32_e32 v238, v223, v223
	v_pk_add_f32 v[90:91], v[96:97], v[96:97] op_sel:[0,1] op_sel_hi:[1,0]
	v_pk_add_f32 v[96:97], v[98:99], v[98:99] op_sel:[0,1] op_sel_hi:[1,0]
	v_pk_fma_f32 v[242:243], v[194:195], v[194:195], v[242:243]
	v_mov_b32_e32 v91, v237
	v_mov_b32_e32 v97, v238
	v_mul_f32_e32 v239, v220, v220
	v_mul_f32_e32 v240, v221, v221
	v_pk_add_f32 v[90:91], v[90:91], v[96:97]
	v_pk_add_f32 v[96:97], v[248:249], v[248:249] op_sel:[0,1] op_sel_hi:[1,0]
	v_pk_add_f32 v[98:99], v[242:243], v[242:243] op_sel:[0,1] op_sel_hi:[1,0]
	v_mov_b32_e32 v97, v239
	v_mov_b32_e32 v99, v240
	v_lshlrev_b32_e32 v198, 16, v206
	v_and_b32_e32 v199, 0xffff0000, v206
	v_lshlrev_b32_e32 v206, 16, v207
	v_and_b32_e32 v207, 0xffff0000, v207
	v_pk_add_f32 v[96:97], v[96:97], v[98:99]
	v_mul_f32_e32 v98, v207, v207
	v_pk_add_f32 v[90:91], v[90:91], v[96:97]
	v_mul_f32_e32 v96, v199, v199
	v_mul_f32_e32 v241, v218, v218
	v_mul_f32_e32 v244, v219, v219
	v_pk_fma_f32 v[96:97], v[198:199], v[198:199], v[96:97] op_sel_hi:[1,1,0]
	v_pk_fma_f32 v[98:99], v[206:207], v[206:207], v[98:99] op_sel_hi:[1,1,0]
	v_mov_b32_e32 v97, v241
	v_mov_b32_e32 v99, v244
	v_pk_add_f32 v[96:97], v[96:97], v[98:99]
	v_mul_f32_e32 v98, v197, v197
	v_mul_f32_e32 v238, v203, v203
	v_mul_f32_e32 v245, v216, v216
	v_mul_f32_e32 v246, v217, v217
	v_pk_fma_f32 v[98:99], v[196:197], v[196:197], v[98:99] op_sel_hi:[1,1,0]
	v_pk_fma_f32 v[238:239], v[202:203], v[202:203], v[238:239] op_sel_hi:[1,1,0]
	v_mov_b32_e32 v99, v245
	v_mov_b32_e32 v239, v246
	v_pk_add_f32 v[98:99], v[98:99], v[238:239]
	s_nop 0
	v_pk_add_f32 v[96:97], v[96:97], v[98:99]
	s_nop 0
	v_pk_add_f32 v[90:91], v[90:91], v[96:97]
	v_mov_b32_e32 v97, v88
	v_mov_b32_e32 v96, v90
	v_mov_b32_e32 v88, v91
	v_pk_add_f32 v[88:89], v[96:97], v[88:89]
	ds_bpermute_b32 v91, v225, v89
	ds_bpermute_b32 v90, v225, v88
	s_waitcnt lgkmcnt(0)
; #define GAS __attribute__((address_space(1)))
; __device__ __forceinline__ f32x4 bf4(const unsigned a, const unsigned b) { return (f32x4){blo(a), bhi(a), blo(b), bhi(b)}; }
; __device__ __forceinline__ void rowpass(const Frame& F, const float* xin32, const unsigned short* xih, const unsigned char* xil, const bf16* Y, float* xo32, unsigned short* xoh, unsigned char* xol, ...
;     ...
;             for (int o = 1; o < 64; o <<= 1) { s0 += __shfl_xor(s0, o); s1 += __shfl_xor(s1, o); }
;             const float r0 = scale * rsqrtf(s0 * (1.f / D) + EPS), r1 = scale * rsqrtf(s1 * (1.f / D) + EPS);
; #pragma unroll
;             for (int j = 0; j < 4; ++j) { x0[2 * j] = x0[2 * j] + bf4(y0[j].x, y0[j].y) * gq[2 * j] * r0; x0[2 * j + 1] = x0[2 * j + 1] + bf4(y0[j].z, y0[j].w) * gq[2 * j + 1] * r0;
;                 x1[2 * j] = x1[2 * j] + bf4(y1[j].x, y1[j].y) * gq[2 * j] * r1; x1[2 * j + 1] = x1[2 * j + 1] + bf4(y1[j].z, y1[j].w) * gq[2 * j + 1] * r1; }
;     ...
;             for (int j = 0; j < 4; ++j) { const f32x4 ga = ((const GAS f32x4*)gpre)[2 * (64 * j + ln)], gb = ((const GAS f32x4*)gpre)[2 * (64 * j + ln) + 1];
	v_pk_add_f32 v[88:89], v[88:89], v[90:91]
	ds_bpermute_b32 v91, v226, v89
	ds_bpermute_b32 v90, v226, v88
	s_waitcnt lgkmcnt(0)
	v_pk_add_f32 v[88:89], v[88:89], v[90:91]
	ds_bpermute_b32 v91, v227, v89
	ds_bpermute_b32 v90, v227, v88
	s_waitcnt lgkmcnt(0)
	v_pk_add_f32 v[88:89], v[88:89], v[90:91]
	ds_bpermute_b32 v91, v234, v89
	ds_bpermute_b32 v90, v234, v88
	s_waitcnt lgkmcnt(0)
	v_pk_add_f32 v[88:89], v[88:89], v[90:91]
	ds_bpermute_b32 v91, v235, v89
	ds_bpermute_b32 v90, v235, v88
	s_waitcnt lgkmcnt(0)
	v_pk_add_f32 v[88:89], v[88:89], v[90:91]
	ds_bpermute_b32 v91, v236, v89
	ds_bpermute_b32 v90, v236, v88
	s_waitcnt lgkmcnt(0)
	v_pk_add_f32 v[88:89], v[88:89], v[90:91]
	s_nop 0
	v_pk_fma_f32 v[88:89], v[88:89], s[6:7], v[172:173] op_sel_hi:[1,0,0]
	s_nop 0
	v_mul_f32_e32 v90, 0x4b800000, v89
	v_cmp_gt_f32_e32 vcc, s90, v89
	v_cmp_gt_f32_e64 s[40:41], s90, v88
	s_nop 0
	v_cndmask_b32_e32 v89, v89, v90, vcc
	v_rsq_f32_e32 v89, v89
	v_mul_f32_e32 v90, 0x4b800000, v88
	v_cndmask_b32_e64 v88, v88, v90, s[40:41]
	v_rsq_f32_e32 v88, v88
	v_mul_f32_e32 v90, 0x45800000, v89
	v_cndmask_b32_e32 v89, v89, v90, vcc
	v_mul_f32_e32 v238, 0.5, v89
	v_mul_f32_e32 v89, 0x45800000, v88
	v_cndmask_b32_e64 v88, v88, v89, s[40:41]
	v_mul_f32_e32 v240, 0.5, v88
	v_mov_b32_e32 v88, v86
	v_mov_b32_e32 v89, v84
	v_mov_b32_e32 v84, v87
	v_pk_mul_f32 v[88:89], v[6:7], v[88:89]
	v_pk_mul_f32 v[84:85], v[8:9], v[84:85]
	s_andn2_b64 vcc, exec, s[58:59]
	v_pk_fma_f32 v[86:87], v[84:85], v[238:239], v[42:43] op_sel_hi:[1,0,1]
	v_pk_fma_f32 v[84:85], v[88:89], v[238:239], v[40:41] op_sel_hi:[1,0,1]
	v_mov_b32_e32 v40, v78
	v_mov_b32_e32 v41, v76
	v_pk_mul_f32 v[40:41], v[2:3], v[40:41]
	v_mov_b32_e32 v76, v79
	v_pk_fma_f32 v[88:89], v[40:41], v[238:239], v[36:37] op_sel_hi:[1,0,1]
	v_mov_b32_e32 v36, v94
	v_mov_b32_e32 v37, v92
	v_pk_mul_f32 v[42:43], v[4:5], v[76:77]
	v_pk_mul_f32 v[36:37], v[6:7], v[36:37]
	v_mov_b32_e32 v92, v95
	v_pk_fma_f32 v[90:91], v[42:43], v[238:239], v[38:39] op_sel_hi:[1,0,1]
	v_pk_mul_f32 v[38:39], v[8:9], v[92:93]
	v_pk_fma_f32 v[92:93], v[36:37], v[240:241], v[52:53] op_sel_hi:[1,0,1]
	v_mov_b32_e32 v36, v82
	v_mov_b32_e32 v37, v80
	v_pk_mul_f32 v[36:37], v[2:3], v[36:37]
	v_mov_b32_e32 v80, v83
	v_pk_fma_f32 v[96:97], v[36:37], v[240:241], v[56:57] op_sel_hi:[1,0,1]
	v_mov_b32_e32 v36, v74
	v_mov_b32_e32 v37, v72
	v_pk_mul_f32 v[36:37], v[14:15], v[36:37]
	v_pk_fma_f32 v[94:95], v[38:39], v[240:241], v[54:55] op_sel_hi:[1,0,1]
	v_pk_mul_f32 v[38:39], v[4:5], v[80:81]
	v_pk_fma_f32 v[80:81], v[36:37], v[238:239], v[48:49] op_sel_hi:[1,0,1]
	v_mov_b32_e32 v36, v70
	v_mov_b32_e32 v37, v68
	v_mov_b32_e32 v72, v75
	v_pk_mul_f32 v[36:37], v[10:11], v[36:37]
	v_pk_fma_f32 v[98:99], v[38:39], v[240:241], v[58:59] op_sel_hi:[1,0,1]
	v_pk_mul_f32 v[38:39], v[16:17], v[72:73]
	v_mov_b32_e32 v68, v71
	v_pk_fma_f32 v[72:73], v[36:37], v[238:239], v[44:45] op_sel_hi:[1,0,1]
	v_mov_b32_e32 v36, v204
	v_mov_b32_e32 v37, v200
	v_pk_fma_f32 v[82:83], v[38:39], v[238:239], v[50:51] op_sel_hi:[1,0,1]
	v_pk_mul_f32 v[38:39], v[12:13], v[68:69]
	v_pk_mul_f32 v[36:37], v[14:15], v[36:37]
	v_mov_b32_e32 v200, v205
	v_pk_fma_f32 v[74:75], v[38:39], v[238:239], v[46:47] op_sel_hi:[1,0,1]
	v_pk_mul_f32 v[38:39], v[16:17], v[200:201]
	v_pk_fma_f32 v[76:77], v[36:37], v[240:241], v[60:61] op_sel_hi:[1,0,1]
	v_mov_b32_e32 v36, v194
	v_mov_b32_e32 v37, v192
	v_mov_b32_e32 v192, v195
	v_pk_fma_f32 v[78:79], v[38:39], v[240:241], v[62:63] op_sel_hi:[1,0,1]
	v_pk_mul_f32 v[36:37], v[10:11], v[36:37]
	v_pk_mul_f32 v[38:39], v[12:13], v[192:193]
	v_pk_fma_f32 v[68:69], v[36:37], v[240:241], v[64:65] op_sel_hi:[1,0,1]
	v_pk_fma_f32 v[70:71], v[38:39], v[240:241], v[66:67] op_sel_hi:[1,0,1]
	v_pk_mul_f32 v[36:37], v[22:23], v[190:191]
	v_pk_mul_f32 v[38:39], v[24:25], v[188:189]
	v_pk_fma_f32 v[64:65], v[36:37], v[238:239], v[104:105] op_sel_hi:[1,0,1]
	v_pk_fma_f32 v[66:67], v[38:39], v[238:239], v[106:107] op_sel_hi:[1,0,1]
	v_pk_mul_f32 v[36:37], v[18:19], v[186:187]
	v_pk_mul_f32 v[38:39], v[20:21], v[162:163]
	v_pk_fma_f32 v[56:57], v[36:37], v[238:239], v[100:101] op_sel_hi:[1,0,1]
	v_pk_fma_f32 v[58:59], v[38:39], v[238:239], v[102:103] op_sel_hi:[1,0,1]
	v_pk_mul_f32 v[36:37], v[22:23], v[198:199]
	v_pk_mul_f32 v[38:39], v[24:25], v[206:207]
	v_pk_fma_f32 v[60:61], v[36:37], v[240:241], v[120:121] op_sel_hi:[1,0,1]
	v_pk_fma_f32 v[62:63], v[38:39], v[240:241], v[122:123] op_sel_hi:[1,0,1]
	v_pk_mul_f32 v[36:37], v[18:19], v[196:197]
	v_pk_mul_f32 v[38:39], v[20:21], v[202:203]
	v_pk_fma_f32 v[52:53], v[36:37], v[240:241], v[124:125] op_sel_hi:[1,0,1]
	v_pk_fma_f32 v[54:55], v[38:39], v[240:241], v[126:127] op_sel_hi:[1,0,1]
	v_pk_mul_f32 v[36:37], v[30:31], v[214:215]
	v_pk_mul_f32 v[38:39], v[32:33], v[212:213]
	v_pk_fma_f32 v[48:49], v[36:37], v[238:239], v[112:113] op_sel_hi:[1,0,1]
	v_pk_fma_f32 v[50:51], v[38:39], v[238:239], v[114:115] op_sel_hi:[1,0,1]
	v_pk_mul_f32 v[36:37], v[26:27], v[210:211]
	v_pk_mul_f32 v[38:39], v[28:29], v[208:209]
	v_pk_fma_f32 v[40:41], v[36:37], v[238:239], v[108:109] op_sel_hi:[1,0,1]
	v_pk_fma_f32 v[42:43], v[38:39], v[238:239], v[110:111] op_sel_hi:[1,0,1]
	v_pk_mul_f32 v[36:37], v[30:31], v[222:223]
	v_pk_mul_f32 v[38:39], v[32:33], v[220:221]
	v_pk_fma_f32 v[44:45], v[36:37], v[240:241], v[128:129] op_sel_hi:[1,0,1]
	v_pk_fma_f32 v[46:47], v[38:39], v[240:241], v[130:131] op_sel_hi:[1,0,1]
	v_pk_mul_f32 v[36:37], v[26:27], v[218:219]
	v_pk_mul_f32 v[38:39], v[28:29], v[216:217]
	v_pk_fma_f32 v[36:37], v[36:37], v[240:241], v[116:117] op_sel_hi:[1,0,1]
	v_pk_fma_f32 v[38:39], v[38:39], v[240:241], v[118:119] op_sel_hi:[1,0,1]
	s_and_b64 vcc, exec, s[60:61]
	s_cbranch_vccz .Lrp3_nog
	global_load_dwordx4 v[186:189], v[132:133], off
	global_load_dwordx4 v[190:193], v[132:133], off offset:16
	global_load_dwordx4 v[194:197], v[132:133], off offset:2048
	global_load_dwordx4 v[198:201], v[132:133], off offset:2064
	global_load_dwordx4 v[202:205], v[134:135], off
	global_load_dwordx4 v[206:209], v[134:135], off offset:16
	global_load_dwordx4 v[210:213], v[136:137], off
	global_load_dwordx4 v[214:217], v[136:137], off offset:16
; #define GAS __attribute__((address_space(1)))
; __device__ __forceinline__ void rowpass(const Frame& F, const float* xin32, const unsigned short* xih, const unsigned char* xil, const bf16* Y, float* xo32, unsigned short* xoh, unsigned char* xol, ...
;     ...
;             if (xo32) { GAS f32x4* xo0 = (GAS f32x4*)(xo32 + (size_t)m * D) + 2 * ln; GAS f32x4* xo1 = (GAS f32x4*)(xo32 + (size_t)m1 * D) + 2 * ln;
; #pragma unroll
;                 for (int j = 0; j < 4; ++j) { xo0[128 * j] = x0[2 * j]; xo0[128 * j + 1] = x0[2 * j + 1]; xo1[128 * j] = x1[2 * j]; xo1[128 * j + 1] = x1[2 * j + 1]; } }
.Lrp3_nog:
	s_andn2_b64 vcc, exec, s[58:59]
	s_cbranch_vccnz .LBB0_852
	v_lshl_add_u64 v[100:101], s[66:67], 0, v[34:35]
	v_lshl_add_u64 v[102:103], s[82:83], 2, v[150:151]
	global_store_dwordx4 v[100:101], v[84:87], off
	global_store_dwordx4 v[100:101], v[88:91], off offset:16
	global_store_dwordx4 v[102:103], v[92:95], off
	global_store_dwordx4 v[102:103], v[96:99], off offset:16
	global_store_dwordx4 v[100:101], v[80:83], off offset:2048
	global_store_dwordx4 v[100:101], v[72:75], off offset:2064
	global_store_dwordx4 v[102:103], v[76:79], off offset:2048
	global_store_dwordx4 v[102:103], v[68:71], off offset:2064
	v_add_co_u32_e32 v100, vcc, s73, v100
	s_nop 1
	v_addc_co_u32_e32 v101, vcc, 0, v101, vcc
	v_add_co_u32_e32 v102, vcc, 0x1000, v102
	global_store_dwordx4 v[100:101], v[64:67], off
	global_store_dwordx4 v[100:101], v[56:59], off offset:16
	v_addc_co_u32_e32 v103, vcc, 0, v103, vcc
	global_store_dwordx4 v[102:103], v[60:63], off
	global_store_dwordx4 v[102:103], v[52:55], off offset:16
	global_store_dwordx4 v[100:101], v[48:51], off offset:2048
	global_store_dwordx4 v[100:101], v[40:43], off offset:2064
	global_store_dwordx4 v[102:103], v[44:47], off offset:2048
	global_store_dwordx4 v[102:103], v[36:39], off offset:2064
	s_cbranch_execnz .LBB0_813

; #define GAS __attribute__((address_space(1)))
; __device__ __forceinline__ void rowpass(const Frame& F, const float* xin32, const unsigned short* xih, const unsigned char* xil, const bf16* Y, float* xo32, unsigned short* xoh, unsigned char* xol, ...
;     ...
;             if (RS) { float m0 = 0.f, mm1 = 0.f;
; #pragma unroll
;                 for (int j = 0; j < 4; ++j) { const f32x4 ga = ((const GAS f32x4*)gpre)[2 * (64 * j + ln)], gb = ((const GAS f32x4*)gpre)[2 * (64 * j + ln) + 1];
;                     const f32x4 a = x0[2 * j] * ga, b = x0[2 * j + 1] * gb, c = x1[2 * j] * ga, d = x1[2 * j + 1] * gb;
;                     m0 = fmaxf(m0, fmaxf(fmaxf(fmaxf(fabsf(a.x), fabsf(a.y)), fmaxf(fabsf(a.z), fabsf(a.w))), fmaxf(fmaxf(fabsf(b.x), fabsf(b.y)), fmaxf(fabsf(b.z), fabsf(b.w)))));
;                     mm1 = fmaxf(mm1, fmaxf(fmaxf(fmaxf(fabsf(c.x), fabsf(c.y)), fmaxf(fabsf(c.z), fabsf(c.w))), fmaxf(fmaxf(fabsf(d.x), fabsf(d.y)), fmaxf(fabsf(d.z), fabsf(d.w))))); }
; #pragma unroll
;                 for (int o = 1; o < 64; o <<= 1) { m0 = fmaxf(m0, __shfl_xor(m0, o)); mm1 = fmaxf(mm1, __shfl_xor(mm1, o)); }
;                 const float h0 = fmaxf(m0 * r0, 1e-30f), h1 = fmaxf(mm1 * r1, 1e-30f); q0 = 127.0f / h0; q1 = 127.0f / h1;
;                 if (ln == 0) { RS[m] = h0 * (1.0f / 127.0f); RS[m1] = h1 * (1.0f / 127.0f); } }
.LBB0_816:
	v_mul_f32_e32 v102, 0x4b800000, v101
	v_cndmask_b32_e64 v101, v101, v102, s[44:45]
	v_mul_f32_e32 v102, 0x4b800000, v100
	v_rsq_f32_e32 v101, v101
	v_cndmask_b32_e64 v100, v100, v102, s[42:43]
	v_rsq_f32_e32 v100, v100
	s_andn2_b64 vcc, exec, s[84:85]
	v_mul_f32_e32 v102, 0x45800000, v101
	v_cndmask_b32_e64 v102, v101, v102, s[44:45]
	v_mul_f32_e32 v101, 0x45800000, v100
	v_cndmask_b32_e64 v100, v100, v101, s[42:43]
	v_mov_b32_e32 v104, v224
	v_mov_b32_e32 v106, v224
	s_cbranch_vccnz .LBB0_820
	s_waitcnt vmcnt(16)
	v_pk_mul_f32 v[116:117], v[90:91], v[192:193]
	v_pk_mul_f32 v[112:113], v[86:87], v[188:189]
	v_pk_mul_f32 v[114:115], v[84:85], v[186:187]
	v_pk_mul_f32 v[118:119], v[88:89], v[190:191]
	v_pk_mul_f32 v[106:107], v[98:99], v[192:193]
	v_max_f32_e64 v103, |v112|, |v113|
	v_max_f32_e64 v112, |v116|, |v117|
	v_pk_mul_f32 v[110:111], v[94:95], v[188:189]
	v_pk_mul_f32 v[108:109], v[92:93], v[186:187]
	v_pk_mul_f32 v[104:105], v[96:97], v[190:191]
	v_max_f32_e64 v101, |v114|, |v115|
	v_max3_f32 v112, |v118|, |v119|, v112
	v_max_f32_e64 v106, |v106|, |v107|
	v_max3_f32 v101, v101, v103, v112
	v_max_f32_e64 v103, |v108|, |v109|
	v_max_f32_e64 v108, |v110|, |v111|
	v_max3_f32 v104, |v104|, |v105|, v106
	v_max3_f32 v103, v103, v108, v104
	v_pk_mul_f32 v[116:117], v[74:75], v[200:201]
	v_pk_mul_f32 v[106:107], v[70:71], v[200:201]
	v_pk_mul_f32 v[112:113], v[82:83], v[196:197]
	v_pk_mul_f32 v[114:115], v[80:81], v[194:195]
	v_pk_mul_f32 v[118:119], v[72:73], v[198:199]
	v_pk_mul_f32 v[110:111], v[78:79], v[196:197]
	v_pk_mul_f32 v[108:109], v[76:77], v[194:195]
	v_pk_mul_f32 v[104:105], v[68:69], v[198:199]
	v_max_f32_e64 v106, |v106|, |v107|
	v_max_f32_e64 v108, |v108|, |v109|
	v_max_f32_e64 v109, |v110|, |v111|
	v_max3_f32 v104, |v104|, |v105|, v106
	v_max3_f32 v104, v108, v109, v104
	v_max3_f32 v103, v103, 0, v104
	v_max_f32_e64 v112, |v112|, |v113|
	v_max_f32_e64 v113, |v116|, |v117|
	v_max_f32_e64 v114, |v114|, |v115|
	v_max3_f32 v113, |v118|, |v119|, v113
	v_max3_f32 v112, v114, v112, v113
	v_max3_f32 v101, v101, 0, v112
	v_pk_mul_f32 v[116:117], v[58:59], v[208:209]
	v_pk_mul_f32 v[106:107], v[54:55], v[208:209]
	v_pk_mul_f32 v[112:113], v[66:67], v[204:205]
	v_pk_mul_f32 v[114:115], v[64:65], v[202:203]
	v_pk_mul_f32 v[118:119], v[56:57], v[206:207]
	v_pk_mul_f32 v[110:111], v[62:63], v[204:205]
	v_pk_mul_f32 v[108:109], v[60:61], v[202:203]
	v_pk_mul_f32 v[104:105], v[52:53], v[206:207]
	v_max_f32_e64 v106, |v106|, |v107|
	v_max_f32_e64 v108, |v108|, |v109|
	v_max_f32_e64 v109, |v110|, |v111|
	v_max3_f32 v104, |v104|, |v105|, v106
	v_max3_f32 v121, v108, v109, v104
	v_max_f32_e64 v112, |v112|, |v113|
	v_max_f32_e64 v113, |v116|, |v117|
	v_max_f32_e64 v114, |v114|, |v115|
	v_max3_f32 v113, |v118|, |v119|, v113
	v_max3_f32 v120, v114, v112, v113
	v_pk_mul_f32 v[116:117], v[42:43], v[216:217]
	v_pk_mul_f32 v[112:113], v[50:51], v[212:213]
	v_pk_mul_f32 v[114:115], v[48:49], v[210:211]
	v_pk_mul_f32 v[118:119], v[40:41], v[214:215]
	v_pk_mul_f32 v[106:107], v[38:39], v[216:217]
	v_max_f32_e64 v112, |v112|, |v113|
	v_max_f32_e64 v113, |v116|, |v117|
	v_pk_mul_f32 v[110:111], v[46:47], v[212:213]
	v_pk_mul_f32 v[108:109], v[44:45], v[210:211]
	v_pk_mul_f32 v[104:105], v[36:37], v[214:215]
	v_max_f32_e64 v114, |v114|, |v115|
	v_max3_f32 v113, |v118|, |v119|, v113
	v_max_f32_e64 v106, |v106|, |v107|
	v_max3_f32 v112, v114, v112, v113
	v_max_f32_e64 v108, |v108|, |v109|
	v_max_f32_e64 v109, |v110|, |v111|
	v_max3_f32 v104, |v104|, |v105|, v106
	v_max3_f32 v101, v101, v120, v112
	v_max3_f32 v104, v108, v109, v104
	v_max3_f32 v103, v103, v121, v104
	ds_bpermute_b32 v104, v225, v101
	s_waitcnt lgkmcnt(0)
	v_max_f32_e32 v104, v104, v104
	v_max_f32_e32 v101, v101, v104
	ds_bpermute_b32 v104, v225, v103
	s_waitcnt lgkmcnt(0)
	v_max_f32_e32 v104, v104, v104
	v_max_f32_e32 v103, v103, v104
	ds_bpermute_b32 v104, v226, v101
	s_waitcnt lgkmcnt(0)
	v_max_f32_e32 v104, v104, v104
	v_max_f32_e32 v101, v101, v104
	ds_bpermute_b32 v104, v226, v103
	s_waitcnt lgkmcnt(0)
	v_max_f32_e32 v104, v104, v104
	v_max_f32_e32 v103, v103, v104
	ds_bpermute_b32 v104, v227, v101
	s_waitcnt lgkmcnt(0)
	v_max_f32_e32 v104, v104, v104
	v_max_f32_e32 v101, v101, v104
	ds_bpermute_b32 v104, v227, v103
	s_waitcnt lgkmcnt(0)
	v_max_f32_e32 v104, v104, v104
	v_max_f32_e32 v103, v103, v104
	ds_bpermute_b32 v104, v234, v101
	s_waitcnt lgkmcnt(0)
	v_max_f32_e32 v104, v104, v104
	v_max_f32_e32 v101, v101, v104
	ds_bpermute_b32 v104, v234, v103
	s_waitcnt lgkmcnt(0)
	v_max_f32_e32 v104, v104, v104
	v_max_f32_e32 v103, v103, v104
	ds_bpermute_b32 v104, v235, v101
	s_waitcnt lgkmcnt(0)
	v_max_f32_e32 v104, v104, v104
	v_max_f32_e32 v101, v101, v104
	ds_bpermute_b32 v104, v235, v103
	s_waitcnt lgkmcnt(0)
	v_max_f32_e32 v104, v104, v104
	v_max_f32_e32 v103, v103, v104
	ds_bpermute_b32 v104, v236, v101
	s_waitcnt lgkmcnt(0)
	v_max_f32_e32 v104, v104, v104
	v_max_f32_e32 v101, v101, v104
	ds_bpermute_b32 v104, v236, v103
	v_mul_f32_e32 v101, v102, v101
	v_max_f32_e32 v101, 0xda24260, v101
	s_waitcnt lgkmcnt(0)
	v_max_f32_e32 v104, v104, v104
	v_max_f32_e32 v103, v103, v104
	v_div_scale_f32 v104, s[12:13], v101, v101, s93
	v_rcp_f32_e32 v105, v104
	v_mul_f32_e32 v103, v100, v103
	v_max_f32_e32 v103, 0xda24260, v103
	v_fma_f32 v106, -v104, v105, 1.0
	v_fmac_f32_e32 v105, v106, v105
	v_div_scale_f32 v106, vcc, s93, v101, s93
	v_mul_f32_e32 v107, v106, v105
	v_fma_f32 v108, -v104, v107, v106
	v_fmac_f32_e32 v107, v108, v105
	v_fma_f32 v104, -v104, v107, v106
	v_div_fmas_f32 v104, v104, v105, v107
	v_div_scale_f32 v105, s[12:13], v103, v103, s93
	v_rcp_f32_e32 v106, v105
	s_nop 0
	v_fma_f32 v107, -v105, v106, 1.0
	v_fmac_f32_e32 v106, v107, v106
	v_div_scale_f32 v107, vcc, s93, v103, s93
	v_mul_f32_e32 v108, v107, v106
	v_fma_f32 v109, -v105, v108, v107
	v_fmac_f32_e32 v108, v109, v106
	v_fma_f32 v105, -v105, v108, v107
	v_div_fmas_f32 v105, v105, v106, v108
	s_and_saveexec_b64 s[42:43], s[38:39]
	s_cbranch_execz .LBB0_819
	s_add_u32 s12, s18, s7
	s_addc_u32 s13, s19, s9
	v_mul_f32_e32 v106, 0x3c010204, v101
	s_add_u32 s34, s18, s10
	v_mul_f32_e32 v107, 0x3c010204, v103
	s_addc_u32 s35, s19, s11
	global_store_dword v35, v106, s[12:13]
	global_store_dword v35, v107, s[34:35]

; #define GAS __attribute__((address_space(1)))
; __device__ __forceinline__ unsigned pk2(float lo, float hi) { f32x2_t v = {lo, hi}; bf16x2_t b = __builtin_convertvector(v, bf16x2_t); return __builtin_bit_cast(unsigned, b); }
; __device__ __forceinline__ void rowpass(const Frame& F, const float* xin32, const unsigned short* xih, const unsigned char* xil, const bf16* Y, float* xo32, unsigned short* xoh, unsigned char* xol, ...
;     ...
; #pragma unroll
;             for (int j = 0; j < 4; ++j) { const f32x4 ga = ((const GAS f32x4*)gpre)[2 * (64 * j + ln)], gb = ((const GAS f32x4*)gpre)[2 * (64 * j + ln) + 1];
;                 const f32x4 a = x0[2 * j] * ga * r0, b = x0[2 * j + 1] * gb * r0, c = x1[2 * j] * ga * r1, d = x1[2 * j + 1] * gb * r1;
;                 if (H) { ho0[64 * j] = (v4u){pk2(a.x, a.y), pk2(a.z, a.w), pk2(b.x, b.y), pk2(b.z, b.w)}; ho1[64 * j] = (v4u){pk2(c.x, c.y), pk2(c.z, c.w), pk2(d.x, d.y), pk2(d.z, d.w)}; }
;                 if (H8) { const f32x4 a8 = a * q0, b8 = b * q0, c8 = c * q1, d8 = d * q1;
.LBB0_820:
	v_cndmask_b32_e64 v101, 0, 1, s[50:51]
	v_lshl_add_u64 v[110:111], s[52:53], 0, v[156:157]
	v_lshl_add_u64 v[108:109], s[82:83], 1, v[152:153]
	v_cmp_ne_u32_e64 s[44:45], 1, v101
	s_andn2_b64 vcc, exec, s[50:51]
	s_waitcnt vmcnt(16)
	v_pk_mul_f32 v[86:87], v[86:87], v[188:189]
	v_pk_mul_f32 v[84:85], v[84:85], v[186:187]
	v_pk_mul_f32 v[90:91], v[90:91], v[192:193]
	v_pk_mul_f32 v[88:89], v[88:89], v[190:191]
	v_pk_mul_f32 v[94:95], v[94:95], v[188:189]
	v_pk_mul_f32 v[92:93], v[92:93], v[186:187]
	v_pk_mul_f32 v[118:119], v[98:99], v[192:193]
	v_pk_mul_f32 v[116:117], v[96:97], v[190:191]
	v_pk_mul_f32 v[112:113], v[102:103], v[84:85] op_sel_hi:[0,1]
	v_pk_mul_f32 v[114:115], v[102:103], v[86:87] op_sel_hi:[0,1]
	v_pk_mul_f32 v[96:97], v[102:103], v[88:89] op_sel_hi:[0,1]
	v_pk_mul_f32 v[98:99], v[102:103], v[90:91] op_sel_hi:[0,1]
	v_pk_mul_f32 v[92:93], v[100:101], v[92:93] op_sel_hi:[0,1]
	v_pk_mul_f32 v[94:95], v[100:101], v[94:95] op_sel_hi:[0,1]
	v_pk_mul_f32 v[90:91], v[100:101], v[116:117] op_sel_hi:[0,1]
	v_pk_mul_f32 v[88:89], v[100:101], v[118:119] op_sel_hi:[0,1]
	s_cbranch_vccnz .LBB0_822
	v_cvt_pk_bf16_f32 v84, v112, v113
	v_cvt_pk_bf16_f32 v85, v114, v115
	v_cvt_pk_bf16_f32 v86, v96, v97
	v_cvt_pk_bf16_f32 v87, v98, v99
	global_store_dwordx4 v[110:111], v[84:87], off
	s_nop 1
	v_cvt_pk_bf16_f32 v84, v92, v93
	v_cvt_pk_bf16_f32 v85, v94, v95
	v_cvt_pk_bf16_f32 v86, v90, v91
	v_cvt_pk_bf16_f32 v87, v88, v89
	global_store_dwordx4 v[108:109], v[84:87], off

; #define GAS __attribute__((address_space(1)))
; __device__ __forceinline__ unsigned pk2(float lo, float hi) { f32x2_t v = {lo, hi}; bf16x2_t b = __builtin_convertvector(v, bf16x2_t); return __builtin_bit_cast(unsigned, b); }
; __device__ __forceinline__ void rowpass(const Frame& F, const float* xin32, const unsigned short* xih, const unsigned char* xil, const bf16* Y, float* xo32, unsigned short* xoh, unsigned char* xol, ...
;     ...
;             for (int j = 0; j < 4; ++j) { const f32x4 ga = ((const GAS f32x4*)gpre)[2 * (64 * j + ln)], gb = ((const GAS f32x4*)gpre)[2 * (64 * j + ln) + 1];
;                 const f32x4 a = x0[2 * j] * ga * r0, b = x0[2 * j + 1] * gb * r0, c = x1[2 * j] * ga * r1, d = x1[2 * j + 1] * gb * r1;
;                 if (H) { ho0[64 * j] = (v4u){pk2(a.x, a.y), pk2(a.z, a.w), pk2(b.x, b.y), pk2(b.z, b.w)}; ho1[64 * j] = (v4u){pk2(c.x, c.y), pk2(c.z, c.w), pk2(d.x, d.y), pk2(d.z, d.w)}; }
;                 if (H8) { const f32x4 a8 = a * q0, b8 = b * q0, c8 = c * q1, d8 = d * q1;
.LBB0_828:
	s_nop 0
	v_mov_b32_e32 v103, v102
	v_mov_b32_e32 v98, v102
	v_mov_b32_e32 v99, v102
	v_mov_b32_e32 v101, v100
	s_and_b64 vcc, exec, s[44:45]
	v_pk_mul_f32 v[74:75], v[74:75], v[200:201]
	v_pk_mul_f32 v[82:83], v[82:83], v[196:197]
	v_pk_mul_f32 v[96:97], v[80:81], v[194:195]
	v_pk_mul_f32 v[80:81], v[98:99], v[82:83]
	v_pk_mul_f32 v[82:83], v[102:103], v[96:97]
	v_pk_mul_f32 v[96:97], v[72:73], v[198:199]
	v_pk_mul_f32 v[78:79], v[78:79], v[196:197]
	v_pk_mul_f32 v[92:93], v[76:77], v[194:195]
	v_mov_b32_e32 v94, v100
	v_mov_b32_e32 v95, v100
	v_pk_mul_f32 v[70:71], v[70:71], v[200:201]
	v_pk_mul_f32 v[88:89], v[68:69], v[198:199]
	v_pk_mul_f32 v[72:73], v[98:99], v[74:75]
	v_pk_mul_f32 v[74:75], v[102:103], v[96:97]
	v_pk_mul_f32 v[76:77], v[94:95], v[78:79]
	v_pk_mul_f32 v[78:79], v[100:101], v[92:93]
	v_pk_mul_f32 v[68:69], v[94:95], v[70:71]
	v_pk_mul_f32 v[70:71], v[100:101], v[88:89]
	s_cbranch_vccnz .LBB0_830
	v_cvt_pk_bf16_f32 v88, v82, v83
	v_cvt_pk_bf16_f32 v89, v80, v81
	v_cvt_pk_bf16_f32 v90, v74, v75
	v_cvt_pk_bf16_f32 v91, v72, v73
	global_store_dwordx4 v[110:111], v[88:91], off offset:1024
	s_nop 1
	v_cvt_pk_bf16_f32 v88, v78, v79
	v_cvt_pk_bf16_f32 v89, v76, v77
	v_cvt_pk_bf16_f32 v90, v70, v71
	v_cvt_pk_bf16_f32 v91, v68, v69
	global_store_dwordx4 v[108:109], v[88:91], off offset:1024

; #define GAS __attribute__((address_space(1)))
; __device__ __forceinline__ unsigned pk2(float lo, float hi) { f32x2_t v = {lo, hi}; bf16x2_t b = __builtin_convertvector(v, bf16x2_t); return __builtin_bit_cast(unsigned, b); }
; __device__ __forceinline__ void rowpass(const Frame& F, const float* xin32, const unsigned short* xih, const unsigned char* xil, const bf16* Y, float* xo32, unsigned short* xoh, unsigned char* xol, ...
;     ...
;             for (int j = 0; j < 4; ++j) { const f32x4 ga = ((const GAS f32x4*)gpre)[2 * (64 * j + ln)], gb = ((const GAS f32x4*)gpre)[2 * (64 * j + ln) + 1];
;                 const f32x4 a = x0[2 * j] * ga * r0, b = x0[2 * j + 1] * gb * r0, c = x1[2 * j] * ga * r1, d = x1[2 * j + 1] * gb * r1;
;                 if (H) { ho0[64 * j] = (v4u){pk2(a.x, a.y), pk2(a.z, a.w), pk2(b.x, b.y), pk2(b.z, b.w)}; ho1[64 * j] = (v4u){pk2(c.x, c.y), pk2(c.z, c.w), pk2(d.x, d.y), pk2(d.z, d.w)}; }
;                 if (H8) { const f32x4 a8 = a * q0, b8 = b * q0, c8 = c * q1, d8 = d * q1;
.LBB0_836:
	s_nop 0
	v_mov_b32_e32 v78, v102
	v_mov_b32_e32 v79, v102
	s_and_b64 vcc, exec, s[44:45]
	v_pk_mul_f32 v[58:59], v[58:59], v[208:209]
	v_pk_mul_f32 v[66:67], v[66:67], v[204:205]
	v_pk_mul_f32 v[76:77], v[64:65], v[202:203]
	v_pk_mul_f32 v[64:65], v[78:79], v[66:67]
	v_pk_mul_f32 v[66:67], v[102:103], v[76:77]
	v_pk_mul_f32 v[76:77], v[56:57], v[206:207]
	v_pk_mul_f32 v[62:63], v[62:63], v[204:205]
	v_pk_mul_f32 v[72:73], v[60:61], v[202:203]
	v_mov_b32_e32 v74, v100
	v_mov_b32_e32 v75, v100
	v_pk_mul_f32 v[54:55], v[54:55], v[208:209]
	v_pk_mul_f32 v[68:69], v[52:53], v[206:207]
	v_pk_mul_f32 v[56:57], v[78:79], v[58:59]
	v_pk_mul_f32 v[58:59], v[102:103], v[76:77]
	v_pk_mul_f32 v[60:61], v[74:75], v[62:63]
	v_pk_mul_f32 v[62:63], v[100:101], v[72:73]
	v_pk_mul_f32 v[52:53], v[74:75], v[54:55]
	v_pk_mul_f32 v[54:55], v[100:101], v[68:69]
	s_cbranch_vccnz .LBB0_838
	v_cvt_pk_bf16_f32 v68, v66, v67
	v_cvt_pk_bf16_f32 v69, v64, v65
	v_cvt_pk_bf16_f32 v70, v58, v59
	v_cvt_pk_bf16_f32 v71, v56, v57
	global_store_dwordx4 v[110:111], v[68:71], off offset:2048
	s_nop 1
	v_cvt_pk_bf16_f32 v68, v62, v63
	v_cvt_pk_bf16_f32 v69, v60, v61
	v_cvt_pk_bf16_f32 v70, v54, v55
	v_cvt_pk_bf16_f32 v71, v52, v53
	global_store_dwordx4 v[108:109], v[68:71], off offset:2048

; #define GAS __attribute__((address_space(1)))
; __device__ __forceinline__ unsigned pk2(float lo, float hi) { f32x2_t v = {lo, hi}; bf16x2_t b = __builtin_convertvector(v, bf16x2_t); return __builtin_bit_cast(unsigned, b); }
; __device__ __forceinline__ void rowpass(const Frame& F, const float* xin32, const unsigned short* xih, const unsigned char* xil, const bf16* Y, float* xo32, unsigned short* xoh, unsigned char* xol, ...
;     ...
;             for (int j = 0; j < 4; ++j) { const f32x4 ga = ((const GAS f32x4*)gpre)[2 * (64 * j + ln)], gb = ((const GAS f32x4*)gpre)[2 * (64 * j + ln) + 1];
;                 const f32x4 a = x0[2 * j] * ga * r0, b = x0[2 * j + 1] * gb * r0, c = x1[2 * j] * ga * r1, d = x1[2 * j + 1] * gb * r1;
;                 if (H) { ho0[64 * j] = (v4u){pk2(a.x, a.y), pk2(a.z, a.w), pk2(b.x, b.y), pk2(b.z, b.w)}; ho1[64 * j] = (v4u){pk2(c.x, c.y), pk2(c.z, c.w), pk2(d.x, d.y), pk2(d.z, d.w)}; }
;                 if (H8) { const f32x4 a8 = a * q0, b8 = b * q0, c8 = c * q1, d8 = d * q1;
.LBB0_844:
	s_nop 0
	v_mov_b32_e32 v62, v102
	v_mov_b32_e32 v63, v102
	s_and_b64 vcc, exec, s[44:45]
	v_pk_mul_f32 v[42:43], v[42:43], v[216:217]
	v_pk_mul_f32 v[50:51], v[50:51], v[212:213]
	v_pk_mul_f32 v[60:61], v[48:49], v[210:211]
	v_pk_mul_f32 v[48:49], v[62:63], v[50:51]
	v_pk_mul_f32 v[50:51], v[102:103], v[60:61]
	v_pk_mul_f32 v[60:61], v[40:41], v[214:215]
	v_pk_mul_f32 v[46:47], v[46:47], v[212:213]
	v_pk_mul_f32 v[56:57], v[44:45], v[210:211]
	v_mov_b32_e32 v58, v100
	v_mov_b32_e32 v59, v100
	v_pk_mul_f32 v[38:39], v[38:39], v[216:217]
	v_pk_mul_f32 v[52:53], v[36:37], v[214:215]
	v_pk_mul_f32 v[40:41], v[62:63], v[42:43]
	v_pk_mul_f32 v[42:43], v[102:103], v[60:61]
	v_pk_mul_f32 v[44:45], v[58:59], v[46:47]
	v_pk_mul_f32 v[46:47], v[100:101], v[56:57]
	v_pk_mul_f32 v[36:37], v[58:59], v[38:39]
	v_pk_mul_f32 v[38:39], v[100:101], v[52:53]
	s_cbranch_vccnz .LBB0_846
	v_cvt_pk_bf16_f32 v52, v50, v51
	v_cvt_pk_bf16_f32 v53, v48, v49
	v_cvt_pk_bf16_f32 v54, v42, v43
	v_cvt_pk_bf16_f32 v55, v40, v41
	global_store_dwordx4 v[110:111], v[52:55], off offset:3072
	s_nop 1
	v_cvt_pk_bf16_f32 v52, v46, v47
	v_cvt_pk_bf16_f32 v53, v44, v45
	v_cvt_pk_bf16_f32 v54, v38, v39
	v_cvt_pk_bf16_f32 v55, v36, v37
	global_store_dwordx4 v[108:109], v[52:55], off offset:3072

; __device__ __forceinline__ unsigned cvt_pk_bf16(float lo, float hi) { f32x2c v = {lo, hi}; bf16x2c b = __builtin_convertvector(v, bf16x2c); return __builtin_bit_cast(unsigned, b); }
;     __device__ __forceinline__ void operator()(const f32x4 (&acc)[2][2][4][2], const Unit& u, int wr, int wc, int fr, int fq) const {
;         const int row0 = u.pm * BM + wr * 64 + fr, col0 = u.pn * BM + wc * 32 + 8 * fq;
; #pragma unroll
;         for (int ai = 0; ai < 2; ++ai)
; #pragma unroll
;             for (int m = 0; m < 4; ++m) { bf16_t* rowp = O + (size_t)(row0 + ai * HALF + m * 16) * ldc + col0;
; #pragma unroll
;                 for (int bj = 0; bj < 2; ++bj) { const f32x4 v0 = acc[ai][bj][m][0], v1 = acc[ai][bj][m][1];
;                     u32x4 w; w.x = cvt_pk_bf16(v0[0], v0[1]); w.y = cvt_pk_bf16(v0[2], v0[3]); w.z = cvt_pk_bf16(v1[0], v1[1]); w.w = cvt_pk_bf16(v1[2], v1[3]);
;                     *(u32x4*)(rowp + bj * HALF) = w; } }
;     }
.LBB0_2141:
	v_lshl_add_u32 v146, s30, 8, v142
	v_lshl_or_b32 v148, s31, 8, v144
	v_ashrrev_i32_e32 v147, 31, v146
	v_ashrrev_i32_e32 v149, 31, v148
	v_lshlrev_b64 v[150:151], 12, v[146:147]
	v_lshl_add_u64 v[150:151], s[26:27], 0, v[150:151]
	v_lshlrev_b64 v[148:149], 1, v[148:149]
	v_lshl_add_u64 v[150:151], v[150:151], 0, v[148:149]
	s_mov_b64 s[30:31], 0x80000
	v_cvt_pk_bf16_f32 v72, v72, v73
	v_cvt_pk_bf16_f32 v73, v74, v75
	v_cvt_pk_bf16_f32 v74, v68, v69
	v_lshl_add_u64 v[68:69], v[150:151], 0, s[30:31]
	s_mov_b32 s30, 0x80000
	v_cvt_pk_bf16_f32 v64, v64, v65
	v_cvt_pk_bf16_f32 v65, v66, v67
	v_cvt_pk_bf16_f32 v66, v60, v61
	v_add_co_u32_e32 v60, vcc, s30, v150
	v_cvt_pk_bf16_f32 v48, v48, v49
	v_cvt_pk_bf16_f32 v49, v50, v51
	v_cvt_pk_bf16_f32 v50, v44, v45
	v_cvt_pk_bf16_f32 v51, v46, v47
	s_mov_b64 s[30:31], 0x90000
	v_addc_co_u32_e32 v61, vcc, 0, v151, vcc
	global_store_dwordx4 v[68:69], v[48:51], off offset:256 sc0 sc1
	v_cvt_pk_bf16_f32 v112, v112, v113
	v_cvt_pk_bf16_f32 v113, v114, v115
	v_lshl_add_u64 v[48:49], v[150:151], 0, s[30:31]
	s_mov_b32 s30, 0x90000
	v_cvt_pk_bf16_f32 v114, v108, v109
	v_or_b32_e32 v108, 16, v146
	v_add_co_u32_e32 v50, vcc, s30, v150
	v_cvt_pk_bf16_f32 v30, v30, v31
	v_cvt_pk_bf16_f32 v31, v32, v33
	v_cvt_pk_bf16_f32 v32, v26, v27
	v_cvt_pk_bf16_f32 v33, v28, v29
	s_mov_b64 s[30:31], 0xa0000
	v_ashrrev_i32_e32 v109, 31, v108
	v_cvt_pk_bf16_f32 v96, v96, v97
	v_cvt_pk_bf16_f32 v97, v98, v99
	v_cvt_pk_bf16_f32 v98, v92, v93
	v_or_b32_e32 v92, 32, v146
	v_addc_co_u32_e32 v51, vcc, 0, v151, vcc
	global_store_dwordx4 v[48:49], v[30:33], off offset:256 sc0 sc1
	v_lshlrev_b64 v[108:109], 12, v[108:109]
	v_ashrrev_i32_e32 v93, 31, v92
	v_lshl_add_u64 v[30:31], v[150:151], 0, s[30:31]
	s_mov_b32 s30, 0xa0000
	v_cvt_pk_bf16_f32 v80, v80, v81
	v_cvt_pk_bf16_f32 v81, v82, v83
	v_cvt_pk_bf16_f32 v82, v76, v77
	v_or_b32_e32 v76, 48, v146
	v_add_co_u32_e32 v32, vcc, s30, v150
	v_cvt_pk_bf16_f32 v14, v14, v15
	v_cvt_pk_bf16_f32 v15, v16, v17
	v_cvt_pk_bf16_f32 v16, v10, v11
	v_cvt_pk_bf16_f32 v17, v12, v13
	s_mov_b64 s[30:31], 0xb0000
	v_cvt_pk_bf16_f32 v115, v110, v111
	v_lshl_add_u64 v[108:109], s[26:27], 0, v[108:109]
	v_lshlrev_b64 v[92:93], 12, v[92:93]
	v_ashrrev_i32_e32 v77, 31, v76
	v_addc_co_u32_e32 v33, vcc, 0, v151, vcc
	global_store_dwordx4 v[30:31], v[14:17], off offset:256 sc0 sc1
	global_store_dwordx4 v[150:151], v[112:115], off offset:256 sc0 sc1
	v_cvt_pk_bf16_f32 v99, v94, v95
	v_lshl_add_u64 v[14:15], v[150:151], 0, s[30:31]
	s_mov_b32 s30, 0xb0000
	v_lshl_add_u64 v[112:113], v[108:109], 0, v[148:149]
	v_lshl_add_u64 v[92:93], s[26:27], 0, v[92:93]
	v_lshlrev_b64 v[76:77], 12, v[76:77]
	v_add_co_u32_e32 v16, vcc, s30, v150
	global_store_dwordx4 v[112:113], v[96:99], off offset:256 sc0 sc1
	v_cvt_pk_bf16_f32 v83, v78, v79
	v_lshl_add_u64 v[76:77], s[26:27], 0, v[76:77]
	v_lshl_add_u64 v[96:97], v[92:93], 0, v[148:149]
	v_addc_co_u32_e32 v17, vcc, 0, v151, vcc
	v_cvt_pk_bf16_f32 v128, v128, v129
	v_cvt_pk_bf16_f32 v129, v130, v131
	v_cvt_pk_bf16_f32 v130, v124, v125
	v_cvt_pk_bf16_f32 v131, v126, v127
	v_cvt_pk_bf16_f32 v108, v120, v121
	v_cvt_pk_bf16_f32 v109, v122, v123
	v_cvt_pk_bf16_f32 v110, v116, v117
	v_cvt_pk_bf16_f32 v111, v118, v119
	v_cvt_pk_bf16_f32 v92, v104, v105
	v_cvt_pk_bf16_f32 v93, v106, v107
	v_cvt_pk_bf16_f32 v94, v100, v101
	v_cvt_pk_bf16_f32 v95, v102, v103
	global_store_dwordx4 v[96:97], v[80:83], off offset:256 sc0 sc1
	v_cvt_pk_bf16_f32 v78, v84, v85
	v_cvt_pk_bf16_f32 v79, v86, v87
	v_lshl_add_u64 v[80:81], v[76:77], 0, v[148:149]
	v_cvt_pk_bf16_f32 v76, v88, v89
	v_cvt_pk_bf16_f32 v77, v90, v91
	v_cvt_pk_bf16_f32 v75, v70, v71
	v_cvt_pk_bf16_f32 v67, v62, v63
	v_cvt_pk_bf16_f32 v44, v56, v57
	v_cvt_pk_bf16_f32 v45, v58, v59
	v_cvt_pk_bf16_f32 v46, v52, v53
	v_cvt_pk_bf16_f32 v47, v54, v55
	v_cvt_pk_bf16_f32 v26, v40, v41
	v_cvt_pk_bf16_f32 v27, v42, v43
	v_cvt_pk_bf16_f32 v28, v36, v37
	v_cvt_pk_bf16_f32 v29, v38, v39
	v_cvt_pk_bf16_f32 v10, v22, v23
	v_cvt_pk_bf16_f32 v11, v24, v25
	v_cvt_pk_bf16_f32 v12, v18, v19
	v_cvt_pk_bf16_f32 v13, v20, v21
	v_cvt_pk_bf16_f32 v6, v6, v7
	v_cvt_pk_bf16_f32 v7, v8, v9
	v_cvt_pk_bf16_f32 v8, v2, v3
	v_cvt_pk_bf16_f32 v9, v4, v5
	s_andn2_b64 vcc, exec, s[38:39]
	s_mov_b64 s[30:31], -1
	global_store_dwordx4 v[150:151], v[128:131], off sc0 sc1
	global_store_dwordx4 v[112:113], v[108:111], off sc0 sc1
	global_store_dwordx4 v[96:97], v[92:95], off sc0 sc1
	global_store_dwordx4 v[80:81], v[76:79], off sc0 sc1
	global_store_dwordx4 v[80:81], v[72:75], off offset:256 sc0 sc1
	global_store_dwordx4 v[60:61], v[64:67], off sc0 sc1
	global_store_dwordx4 v[50:51], v[44:47], off sc0 sc1
	global_store_dwordx4 v[32:33], v[26:29], off sc0 sc1
	global_store_dwordx4 v[16:17], v[10:13], off sc0 sc1
	global_store_dwordx4 v[14:15], v[6:9], off offset:256 sc0 sc1
	s_cbranch_vccnz .LBB0_2130
	s_andn2_b64 vcc, exec, s[18:19]
	s_cbranch_vccnz .LBB0_2129
	s_barrier
	s_branch .LBB0_2129
